# pool unit: the grid-size scalar load for the unit-loop advance is issued at unit start instead of after the unit's last barrier
# baseline (speedup 1.0000x reference)
.LBB0_117:
	v_readlane_b32 s64, v253, 1
	v_readlane_b32 s65, v253, 2
	s_and_b32 s0, s55, -4
	s_ashr_i32 s1, s0, 31
	s_lshl_b64 s[6:7], s[0:1], 17
	s_or_b32 s10, s0, 1
	s_or_b32 s0, s0, 2
	s_or_b32 s18, s55, 3
	s_ashr_i32 s11, s10, 31
	s_ashr_i32 s1, s0, 31
	s_ashr_i32 s19, s18, 31
	s_lshl_b64 s[10:11], s[10:11], 17
	s_lshl_b64 s[0:1], s[0:1], 17
	s_lshl_b64 s[18:19], s[18:19], 17
	v_readlane_b32 s20, v253, 11
	v_readlane_b32 s21, v253, 12
	s_add_u32 s26, s20, s18
	s_addc_u32 s27, s21, s19
	s_add_u32 s38, s80, s58
	s_addc_u32 s39, s81, s59
	s_add_u32 s40, s82, s58
	s_addc_u32 s41, s83, s59
	s_add_u32 s34, s20, s0
	s_addc_u32 s35, s21, s1
	v_writelane_b32 v255, s56, 27
	s_add_u32 s52, s20, s10
	s_addc_u32 s53, s21, s11
	v_writelane_b32 v255, s57, 28
	s_add_u32 s54, s20, s6
	v_readlane_b32 s22, v255, 32
	s_addc_u32 s55, s21, s7
	v_readlane_b32 s20, v253, 0
	v_readlane_b32 s23, v255, 33
	s_movk_i32 s61, 0xfff
	s_nop 2
	s_load_dword s63, s[64:65], 0x10
	s_branch .LBB0_119

.LBB0_118:
	s_waitcnt lgkmcnt(0)
	s_lshr_b32 s0, s63, 16
	s_cmp_lg_u32 s0, 0
	s_cselect_b64 s[0:1], -1, 0
	s_cmp_lg_u64 s[0:1], 0
	s_addc_u32 s20, s20, s94
	s_cmpk_gt_i32 s20, 0xff
	s_cbranch_scc1 .Lmix_pool_done
